# P5 final epilogue hand-scheduled: all 16 gate_b loads in flight, stores no longer serialise with the next gate loads
# baseline (speedup 1.0000x reference)
.LBB0_707:
	s_add_i32 s21, s5, s58
	v_or_b32_e32 v156, s21, v160
	v_or_b32_e32 v208, s21, v163
	v_lshlrev_b32_e32 v157, 12, v156
	v_lshl_add_u32 v157, v154, 1, v157
	s_mov_b64 s[20:21], s[26:27]
	global_load_dwordx4 v[168:171], v157, s[20:21] offset:2048
	global_load_dwordx4 v[172:175], v157, s[20:21] offset:2112
	s_add_u32 s20, s26, 0x10000
	s_addc_u32 s21, s27, 0
	global_load_dwordx4 v[176:179], v157, s[20:21] offset:2048
	global_load_dwordx4 v[180:183], v157, s[20:21] offset:2112
	s_add_u32 s20, s26, 0x20000
	s_addc_u32 s21, s27, 0
	global_load_dwordx4 v[184:187], v157, s[20:21] offset:2048
	global_load_dwordx4 v[188:191], v157, s[20:21] offset:2112
	s_add_u32 s20, s26, 0x30000
	s_addc_u32 s21, s27, 0
	global_load_dwordx4 v[192:195], v157, s[20:21] offset:2048
	global_load_dwordx4 v[196:199], v157, s[20:21] offset:2112
	s_add_u32 s20, s26, 0x80000
	s_addc_u32 s21, s27, 0
	global_load_dwordx4 v[200:203], v157, s[20:21] offset:2048
	global_load_dwordx4 v[204:207], v157, s[20:21] offset:2112
	s_add_u32 s20, s26, 0x90000
	s_addc_u32 s21, s27, 0
	global_load_dwordx4 v[218:221], v157, s[20:21] offset:2048
	global_load_dwordx4 v[222:225], v157, s[20:21] offset:2112
	s_add_u32 s20, s26, 0xa0000
	s_addc_u32 s21, s27, 0
	global_load_dwordx4 v[226:229], v157, s[20:21] offset:2048
	global_load_dwordx4 v[230:233], v157, s[20:21] offset:2112
	s_add_u32 s20, s26, 0xb0000
	s_addc_u32 s21, s27, 0
	global_load_dwordx4 v[234:237], v157, s[20:21] offset:2048
	global_load_dwordx4 v[238:241], v157, s[20:21] offset:2112
	v_ashrrev_i32_e32 v209, 31, v208
	v_lshlrev_b64 v[208:209], 11, v[208:209]
	s_ashr_i32 s5, s4, 31
	v_lshl_add_u64 v[208:209], s[94:95], 0, v[208:209]
	v_lshl_add_u64 v[208:209], s[4:5], 1, v[208:209]
	v_lshl_add_u64 v[208:209], v[208:209], 0, s[8:9]
	v_lshl_add_u64 v[208:209], v[208:209], 0, v[144:145]
	s_mov_b32 s21, 0
	s_waitcnt vmcnt(14)
	v_lshlrev_b32_e32 v128, 16, v168
	v_and_b32_e32 v129, 0xffff0000, v168
	v_lshlrev_b32_e32 v130, 16, v169
	v_and_b32_e32 v131, 0xffff0000, v169
	v_lshlrev_b32_e32 v132, 16, v170
	v_and_b32_e32 v133, 0xffff0000, v170
	v_lshlrev_b32_e32 v134, 16, v171
	v_and_b32_e32 v135, 0xffff0000, v171
	v_lshlrev_b32_e32 v168, 16, v172
	v_and_b32_e32 v169, 0xffff0000, v172
	v_lshlrev_b32_e32 v170, 16, v173
	v_and_b32_e32 v171, 0xffff0000, v173
	v_lshlrev_b32_e32 v172, 16, v174
	v_and_b32_e32 v173, 0xffff0000, v174
	v_lshlrev_b32_e32 v174, 16, v175
	v_and_b32_e32 v175, 0xffff0000, v175
	v_max_f32_e32 v128, 0xda24260, v128
	v_max_f32_e32 v129, 0xda24260, v129
	v_max_f32_e32 v130, 0xda24260, v130
	v_max_f32_e32 v131, 0xda24260, v131
	v_max_f32_e32 v132, 0xda24260, v132
	v_max_f32_e32 v133, 0xda24260, v133
	v_max_f32_e32 v134, 0xda24260, v134
	v_max_f32_e32 v135, 0xda24260, v135
	v_max_f32_e32 v168, 0xda24260, v168
	v_max_f32_e32 v169, 0xda24260, v169
	v_max_f32_e32 v170, 0xda24260, v170
	v_max_f32_e32 v171, 0xda24260, v171
	v_max_f32_e32 v172, 0xda24260, v172
	v_max_f32_e32 v173, 0xda24260, v173
	v_max_f32_e32 v174, 0xda24260, v174
	v_max_f32_e32 v175, 0xda24260, v175
	v_pk_mul_f32 v[124:125], v[124:125], v[128:129]
	v_pk_mul_f32 v[126:127], v[126:127], v[130:131]
	v_pk_mul_f32 v[120:121], v[120:121], v[132:133]
	v_pk_mul_f32 v[122:123], v[122:123], v[134:135]
	v_pk_mul_f32 v[116:117], v[116:117], v[168:169]
	v_pk_mul_f32 v[118:119], v[118:119], v[170:171]
	v_pk_mul_f32 v[112:113], v[112:113], v[172:173]
	v_pk_mul_f32 v[114:115], v[114:115], v[174:175]
	v_cvt_pk_bf16_f32 v168, v124, v125
	v_cvt_pk_bf16_f32 v169, v126, v127
	v_cvt_pk_bf16_f32 v170, v120, v121
	v_cvt_pk_bf16_f32 v171, v122, v123
	v_cvt_pk_bf16_f32 v172, v116, v117
	v_cvt_pk_bf16_f32 v173, v118, v119
	v_cvt_pk_bf16_f32 v174, v112, v113
	v_cvt_pk_bf16_f32 v175, v114, v115
	ds_write_b128 v166, v[168:171]
	ds_write_b128 v166, v[172:175] offset:64
	ds_read_b128 v[168:171], v167
	ds_read_b128 v[172:175], v167 offset:1152
	s_mov_b32 s20, 0x4000
	v_lshl_add_u64 v[122:123], v[208:209], 0, s[20:21]
	s_waitcnt lgkmcnt(1)
	global_store_dwordx4 v[208:209], v[168:171], off
	s_waitcnt lgkmcnt(0)
	global_store_dwordx4 v[122:123], v[172:175], off
	s_waitcnt vmcnt(14)
	v_lshlrev_b32_e32 v128, 16, v176
	v_and_b32_e32 v129, 0xffff0000, v176
	v_lshlrev_b32_e32 v130, 16, v177
	v_and_b32_e32 v131, 0xffff0000, v177
	v_lshlrev_b32_e32 v132, 16, v178
	v_and_b32_e32 v133, 0xffff0000, v178
	v_lshlrev_b32_e32 v134, 16, v179
	v_and_b32_e32 v135, 0xffff0000, v179
	v_lshlrev_b32_e32 v176, 16, v180
	v_and_b32_e32 v177, 0xffff0000, v180
	v_lshlrev_b32_e32 v178, 16, v181
	v_and_b32_e32 v179, 0xffff0000, v181
	v_lshlrev_b32_e32 v180, 16, v182
	v_and_b32_e32 v181, 0xffff0000, v182
	v_lshlrev_b32_e32 v182, 16, v183
	v_and_b32_e32 v183, 0xffff0000, v183
	v_max_f32_e32 v128, 0xda24260, v128
	v_max_f32_e32 v129, 0xda24260, v129
	v_max_f32_e32 v130, 0xda24260, v130
	v_max_f32_e32 v131, 0xda24260, v131
	v_max_f32_e32 v132, 0xda24260, v132
	v_max_f32_e32 v133, 0xda24260, v133
	v_max_f32_e32 v134, 0xda24260, v134
	v_max_f32_e32 v135, 0xda24260, v135
	v_max_f32_e32 v176, 0xda24260, v176
	v_max_f32_e32 v177, 0xda24260, v177
	v_max_f32_e32 v178, 0xda24260, v178
	v_max_f32_e32 v179, 0xda24260, v179
	v_max_f32_e32 v180, 0xda24260, v180
	v_max_f32_e32 v181, 0xda24260, v181
	v_max_f32_e32 v182, 0xda24260, v182
	v_max_f32_e32 v183, 0xda24260, v183
	v_pk_mul_f32 v[108:109], v[108:109], v[128:129]
	v_pk_mul_f32 v[110:111], v[110:111], v[130:131]
	v_pk_mul_f32 v[104:105], v[104:105], v[132:133]
	v_pk_mul_f32 v[106:107], v[106:107], v[134:135]
	v_pk_mul_f32 v[100:101], v[100:101], v[176:177]
	v_pk_mul_f32 v[102:103], v[102:103], v[178:179]
	v_pk_mul_f32 v[96:97], v[96:97], v[180:181]
	v_pk_mul_f32 v[98:99], v[98:99], v[182:183]
	v_cvt_pk_bf16_f32 v176, v108, v109
	v_cvt_pk_bf16_f32 v177, v110, v111
	v_cvt_pk_bf16_f32 v178, v104, v105
	v_cvt_pk_bf16_f32 v179, v106, v107
	v_cvt_pk_bf16_f32 v180, v100, v101
	v_cvt_pk_bf16_f32 v181, v102, v103
	v_cvt_pk_bf16_f32 v182, v96, v97
	v_cvt_pk_bf16_f32 v183, v98, v99
	ds_write_b128 v166, v[176:179]
	ds_write_b128 v166, v[180:183] offset:64
	ds_read_b128 v[176:179], v167
	ds_read_b128 v[180:183], v167 offset:1152
	s_mov_b32 s20, 0x8000
	v_lshl_add_u64 v[104:105], v[208:209], 0, s[20:21]
	s_mov_b32 s20, 0xc000
	v_lshl_add_u64 v[106:107], v[208:209], 0, s[20:21]
	s_waitcnt lgkmcnt(1)
	global_store_dwordx4 v[104:105], v[176:179], off
	s_waitcnt lgkmcnt(0)
	global_store_dwordx4 v[106:107], v[180:183], off
	s_waitcnt vmcnt(14)
	v_lshlrev_b32_e32 v128, 16, v184
	v_and_b32_e32 v129, 0xffff0000, v184
	v_lshlrev_b32_e32 v130, 16, v185
	v_and_b32_e32 v131, 0xffff0000, v185
	v_lshlrev_b32_e32 v132, 16, v186
	v_and_b32_e32 v133, 0xffff0000, v186
	v_lshlrev_b32_e32 v134, 16, v187
	v_and_b32_e32 v135, 0xffff0000, v187
	v_lshlrev_b32_e32 v184, 16, v188
	v_and_b32_e32 v185, 0xffff0000, v188
	v_lshlrev_b32_e32 v186, 16, v189
	v_and_b32_e32 v187, 0xffff0000, v189
	v_lshlrev_b32_e32 v188, 16, v190
	v_and_b32_e32 v189, 0xffff0000, v190
	v_lshlrev_b32_e32 v190, 16, v191
	v_and_b32_e32 v191, 0xffff0000, v191
	v_max_f32_e32 v128, 0xda24260, v128
	v_max_f32_e32 v129, 0xda24260, v129
	v_max_f32_e32 v130, 0xda24260, v130
	v_max_f32_e32 v131, 0xda24260, v131
	v_max_f32_e32 v132, 0xda24260, v132
	v_max_f32_e32 v133, 0xda24260, v133
	v_max_f32_e32 v134, 0xda24260, v134
	v_max_f32_e32 v135, 0xda24260, v135
	v_max_f32_e32 v184, 0xda24260, v184
	v_max_f32_e32 v185, 0xda24260, v185
	v_max_f32_e32 v186, 0xda24260, v186
	v_max_f32_e32 v187, 0xda24260, v187
	v_max_f32_e32 v188, 0xda24260, v188
	v_max_f32_e32 v189, 0xda24260, v189
	v_max_f32_e32 v190, 0xda24260, v190
	v_max_f32_e32 v191, 0xda24260, v191
	v_pk_mul_f32 v[92:93], v[92:93], v[128:129]
	v_pk_mul_f32 v[94:95], v[94:95], v[130:131]
	v_pk_mul_f32 v[88:89], v[88:89], v[132:133]
	v_pk_mul_f32 v[90:91], v[90:91], v[134:135]
	v_pk_mul_f32 v[84:85], v[84:85], v[184:185]
	v_pk_mul_f32 v[86:87], v[86:87], v[186:187]
	v_pk_mul_f32 v[80:81], v[80:81], v[188:189]
	v_pk_mul_f32 v[82:83], v[82:83], v[190:191]
	v_cvt_pk_bf16_f32 v184, v92, v93
	v_cvt_pk_bf16_f32 v185, v94, v95
	v_cvt_pk_bf16_f32 v186, v88, v89
	v_cvt_pk_bf16_f32 v187, v90, v91
	v_cvt_pk_bf16_f32 v188, v84, v85
	v_cvt_pk_bf16_f32 v189, v86, v87
	v_cvt_pk_bf16_f32 v190, v80, v81
	v_cvt_pk_bf16_f32 v191, v82, v83
	ds_write_b128 v166, v[184:187]
	ds_write_b128 v166, v[188:191] offset:64
	ds_read_b128 v[184:187], v167
	ds_read_b128 v[188:191], v167 offset:1152
	s_mov_b32 s20, 0x10000
	v_lshl_add_u64 v[88:89], v[208:209], 0, s[20:21]
	s_mov_b32 s20, 0x14000
	v_lshl_add_u64 v[90:91], v[208:209], 0, s[20:21]
	s_waitcnt lgkmcnt(1)
	global_store_dwordx4 v[88:89], v[184:187], off
	s_waitcnt lgkmcnt(0)
	global_store_dwordx4 v[90:91], v[188:191], off
	s_waitcnt vmcnt(14)
	v_lshlrev_b32_e32 v128, 16, v192
	v_and_b32_e32 v129, 0xffff0000, v192
	v_lshlrev_b32_e32 v130, 16, v193
	v_and_b32_e32 v131, 0xffff0000, v193
	v_lshlrev_b32_e32 v132, 16, v194
	v_and_b32_e32 v133, 0xffff0000, v194
	v_lshlrev_b32_e32 v134, 16, v195
	v_and_b32_e32 v135, 0xffff0000, v195
	v_lshlrev_b32_e32 v192, 16, v196
	v_and_b32_e32 v193, 0xffff0000, v196
	v_lshlrev_b32_e32 v194, 16, v197
	v_and_b32_e32 v195, 0xffff0000, v197
	v_lshlrev_b32_e32 v196, 16, v198
	v_and_b32_e32 v197, 0xffff0000, v198
	v_lshlrev_b32_e32 v198, 16, v199
	v_and_b32_e32 v199, 0xffff0000, v199
	v_max_f32_e32 v128, 0xda24260, v128
	v_max_f32_e32 v129, 0xda24260, v129
	v_max_f32_e32 v130, 0xda24260, v130
	v_max_f32_e32 v131, 0xda24260, v131
	v_max_f32_e32 v132, 0xda24260, v132
	v_max_f32_e32 v133, 0xda24260, v133
	v_max_f32_e32 v134, 0xda24260, v134
	v_max_f32_e32 v135, 0xda24260, v135
	v_max_f32_e32 v192, 0xda24260, v192
	v_max_f32_e32 v193, 0xda24260, v193
	v_max_f32_e32 v194, 0xda24260, v194
	v_max_f32_e32 v195, 0xda24260, v195
	v_max_f32_e32 v196, 0xda24260, v196
	v_max_f32_e32 v197, 0xda24260, v197
	v_max_f32_e32 v198, 0xda24260, v198
	v_max_f32_e32 v199, 0xda24260, v199
	v_pk_mul_f32 v[76:77], v[76:77], v[128:129]
	v_pk_mul_f32 v[78:79], v[78:79], v[130:131]
	v_pk_mul_f32 v[72:73], v[72:73], v[132:133]
	v_pk_mul_f32 v[74:75], v[74:75], v[134:135]
	v_pk_mul_f32 v[68:69], v[68:69], v[192:193]
	v_pk_mul_f32 v[70:71], v[70:71], v[194:195]
	v_pk_mul_f32 v[64:65], v[64:65], v[196:197]
	v_pk_mul_f32 v[66:67], v[66:67], v[198:199]
	v_cvt_pk_bf16_f32 v192, v76, v77
	v_cvt_pk_bf16_f32 v193, v78, v79
	v_cvt_pk_bf16_f32 v194, v72, v73
	v_cvt_pk_bf16_f32 v195, v74, v75
	v_cvt_pk_bf16_f32 v196, v68, v69
	v_cvt_pk_bf16_f32 v197, v70, v71
	v_cvt_pk_bf16_f32 v198, v64, v65
	v_cvt_pk_bf16_f32 v199, v66, v67
	ds_write_b128 v166, v[192:195]
	ds_write_b128 v166, v[196:199] offset:64
	ds_read_b128 v[192:195], v167
	ds_read_b128 v[196:199], v167 offset:1152
	s_mov_b32 s20, 0x18000
	v_lshl_add_u64 v[72:73], v[208:209], 0, s[20:21]
	s_mov_b32 s20, 0x1c000
	v_lshl_add_u64 v[74:75], v[208:209], 0, s[20:21]
	s_waitcnt lgkmcnt(1)
	global_store_dwordx4 v[72:73], v[192:195], off
	s_waitcnt lgkmcnt(0)
	global_store_dwordx4 v[74:75], v[196:199], off
	s_waitcnt vmcnt(14)
	v_lshlrev_b32_e32 v128, 16, v200
	v_and_b32_e32 v129, 0xffff0000, v200
	v_lshlrev_b32_e32 v130, 16, v201
	v_and_b32_e32 v131, 0xffff0000, v201
	v_lshlrev_b32_e32 v132, 16, v202
	v_and_b32_e32 v133, 0xffff0000, v202
	v_lshlrev_b32_e32 v134, 16, v203
	v_and_b32_e32 v135, 0xffff0000, v203
	v_lshlrev_b32_e32 v200, 16, v204
	v_and_b32_e32 v201, 0xffff0000, v204
	v_lshlrev_b32_e32 v202, 16, v205
	v_and_b32_e32 v203, 0xffff0000, v205
	v_lshlrev_b32_e32 v204, 16, v206
	v_and_b32_e32 v205, 0xffff0000, v206
	v_lshlrev_b32_e32 v206, 16, v207
	v_and_b32_e32 v207, 0xffff0000, v207
	v_max_f32_e32 v128, 0xda24260, v128
	v_max_f32_e32 v129, 0xda24260, v129
	v_max_f32_e32 v130, 0xda24260, v130
	v_max_f32_e32 v131, 0xda24260, v131
	v_max_f32_e32 v132, 0xda24260, v132
	v_max_f32_e32 v133, 0xda24260, v133
	v_max_f32_e32 v134, 0xda24260, v134
	v_max_f32_e32 v135, 0xda24260, v135
	v_max_f32_e32 v200, 0xda24260, v200
	v_max_f32_e32 v201, 0xda24260, v201
	v_max_f32_e32 v202, 0xda24260, v202
	v_max_f32_e32 v203, 0xda24260, v203
	v_max_f32_e32 v204, 0xda24260, v204
	v_max_f32_e32 v205, 0xda24260, v205
	v_max_f32_e32 v206, 0xda24260, v206
	v_max_f32_e32 v207, 0xda24260, v207
	v_pk_mul_f32 v[60:61], v[60:61], v[128:129]
	v_pk_mul_f32 v[62:63], v[62:63], v[130:131]
	v_pk_mul_f32 v[56:57], v[56:57], v[132:133]
	v_pk_mul_f32 v[58:59], v[58:59], v[134:135]
	v_pk_mul_f32 v[52:53], v[52:53], v[200:201]
	v_pk_mul_f32 v[54:55], v[54:55], v[202:203]
	v_pk_mul_f32 v[48:49], v[48:49], v[204:205]
	v_pk_mul_f32 v[50:51], v[50:51], v[206:207]
	v_cvt_pk_bf16_f32 v200, v60, v61
	v_cvt_pk_bf16_f32 v201, v62, v63
	v_cvt_pk_bf16_f32 v202, v56, v57
	v_cvt_pk_bf16_f32 v203, v58, v59
	v_cvt_pk_bf16_f32 v204, v52, v53
	v_cvt_pk_bf16_f32 v205, v54, v55
	v_cvt_pk_bf16_f32 v206, v48, v49
	v_cvt_pk_bf16_f32 v207, v50, v51
	ds_write_b128 v166, v[200:203]
	ds_write_b128 v166, v[204:207] offset:64
	ds_read_b128 v[200:203], v167
	ds_read_b128 v[204:207], v167 offset:1152
	s_mov_b32 s20, 0x40000
	v_lshl_add_u64 v[56:57], v[208:209], 0, s[20:21]
	s_mov_b32 s20, 0x44000
	v_lshl_add_u64 v[58:59], v[208:209], 0, s[20:21]
	s_waitcnt lgkmcnt(1)
	global_store_dwordx4 v[56:57], v[200:203], off
	s_waitcnt lgkmcnt(0)
	global_store_dwordx4 v[58:59], v[204:207], off
	s_waitcnt vmcnt(14)
	v_lshlrev_b32_e32 v128, 16, v218
	v_and_b32_e32 v129, 0xffff0000, v218
	v_lshlrev_b32_e32 v130, 16, v219
	v_and_b32_e32 v131, 0xffff0000, v219
	v_lshlrev_b32_e32 v132, 16, v220
	v_and_b32_e32 v133, 0xffff0000, v220
	v_lshlrev_b32_e32 v134, 16, v221
	v_and_b32_e32 v135, 0xffff0000, v221
	v_lshlrev_b32_e32 v218, 16, v222
	v_and_b32_e32 v219, 0xffff0000, v222
	v_lshlrev_b32_e32 v220, 16, v223
	v_and_b32_e32 v221, 0xffff0000, v223
	v_lshlrev_b32_e32 v222, 16, v224
	v_and_b32_e32 v223, 0xffff0000, v224
	v_lshlrev_b32_e32 v224, 16, v225
	v_and_b32_e32 v225, 0xffff0000, v225
	v_max_f32_e32 v128, 0xda24260, v128
	v_max_f32_e32 v129, 0xda24260, v129
	v_max_f32_e32 v130, 0xda24260, v130
	v_max_f32_e32 v131, 0xda24260, v131
	v_max_f32_e32 v132, 0xda24260, v132
	v_max_f32_e32 v133, 0xda24260, v133
	v_max_f32_e32 v134, 0xda24260, v134
	v_max_f32_e32 v135, 0xda24260, v135
	v_max_f32_e32 v218, 0xda24260, v218
	v_max_f32_e32 v219, 0xda24260, v219
	v_max_f32_e32 v220, 0xda24260, v220
	v_max_f32_e32 v221, 0xda24260, v221
	v_max_f32_e32 v222, 0xda24260, v222
	v_max_f32_e32 v223, 0xda24260, v223
	v_max_f32_e32 v224, 0xda24260, v224
	v_max_f32_e32 v225, 0xda24260, v225
	v_pk_mul_f32 v[44:45], v[44:45], v[128:129]
	v_pk_mul_f32 v[46:47], v[46:47], v[130:131]
	v_pk_mul_f32 v[40:41], v[40:41], v[132:133]
	v_pk_mul_f32 v[42:43], v[42:43], v[134:135]
	v_pk_mul_f32 v[36:37], v[36:37], v[218:219]
	v_pk_mul_f32 v[38:39], v[38:39], v[220:221]
	v_pk_mul_f32 v[32:33], v[32:33], v[222:223]
	v_pk_mul_f32 v[34:35], v[34:35], v[224:225]
	v_cvt_pk_bf16_f32 v218, v44, v45
	v_cvt_pk_bf16_f32 v219, v46, v47
	v_cvt_pk_bf16_f32 v220, v40, v41
	v_cvt_pk_bf16_f32 v221, v42, v43
	v_cvt_pk_bf16_f32 v222, v36, v37
	v_cvt_pk_bf16_f32 v223, v38, v39
	v_cvt_pk_bf16_f32 v224, v32, v33
	v_cvt_pk_bf16_f32 v225, v34, v35
	ds_write_b128 v166, v[218:221]
	ds_write_b128 v166, v[222:225] offset:64
	ds_read_b128 v[218:221], v167
	ds_read_b128 v[222:225], v167 offset:1152
	s_mov_b32 s20, 0x48000
	v_lshl_add_u64 v[40:41], v[208:209], 0, s[20:21]
	s_mov_b32 s20, 0x4c000
	v_lshl_add_u64 v[42:43], v[208:209], 0, s[20:21]
	s_waitcnt lgkmcnt(1)
	global_store_dwordx4 v[40:41], v[218:221], off
	s_waitcnt lgkmcnt(0)
	global_store_dwordx4 v[42:43], v[222:225], off
	s_waitcnt vmcnt(14)
	v_lshlrev_b32_e32 v128, 16, v226
	v_and_b32_e32 v129, 0xffff0000, v226
	v_lshlrev_b32_e32 v130, 16, v227
	v_and_b32_e32 v131, 0xffff0000, v227
	v_lshlrev_b32_e32 v132, 16, v228
	v_and_b32_e32 v133, 0xffff0000, v228
	v_lshlrev_b32_e32 v134, 16, v229
	v_and_b32_e32 v135, 0xffff0000, v229
	v_lshlrev_b32_e32 v226, 16, v230
	v_and_b32_e32 v227, 0xffff0000, v230
	v_lshlrev_b32_e32 v228, 16, v231
	v_and_b32_e32 v229, 0xffff0000, v231
	v_lshlrev_b32_e32 v230, 16, v232
	v_and_b32_e32 v231, 0xffff0000, v232
	v_lshlrev_b32_e32 v232, 16, v233
	v_and_b32_e32 v233, 0xffff0000, v233
	v_max_f32_e32 v128, 0xda24260, v128
	v_max_f32_e32 v129, 0xda24260, v129
	v_max_f32_e32 v130, 0xda24260, v130
	v_max_f32_e32 v131, 0xda24260, v131
	v_max_f32_e32 v132, 0xda24260, v132
	v_max_f32_e32 v133, 0xda24260, v133
	v_max_f32_e32 v134, 0xda24260, v134
	v_max_f32_e32 v135, 0xda24260, v135
	v_max_f32_e32 v226, 0xda24260, v226
	v_max_f32_e32 v227, 0xda24260, v227
	v_max_f32_e32 v228, 0xda24260, v228
	v_max_f32_e32 v229, 0xda24260, v229
	v_max_f32_e32 v230, 0xda24260, v230
	v_max_f32_e32 v231, 0xda24260, v231
	v_max_f32_e32 v232, 0xda24260, v232
	v_max_f32_e32 v233, 0xda24260, v233
	v_pk_mul_f32 v[28:29], v[28:29], v[128:129]
	v_pk_mul_f32 v[30:31], v[30:31], v[130:131]
	v_pk_mul_f32 v[24:25], v[24:25], v[132:133]
	v_pk_mul_f32 v[26:27], v[26:27], v[134:135]
	v_pk_mul_f32 v[20:21], v[20:21], v[226:227]
	v_pk_mul_f32 v[22:23], v[22:23], v[228:229]
	v_pk_mul_f32 v[16:17], v[16:17], v[230:231]
	v_pk_mul_f32 v[18:19], v[18:19], v[232:233]
	v_cvt_pk_bf16_f32 v226, v28, v29
	v_cvt_pk_bf16_f32 v227, v30, v31
	v_cvt_pk_bf16_f32 v228, v24, v25
	v_cvt_pk_bf16_f32 v229, v26, v27
	v_cvt_pk_bf16_f32 v230, v20, v21
	v_cvt_pk_bf16_f32 v231, v22, v23
	v_cvt_pk_bf16_f32 v232, v16, v17
	v_cvt_pk_bf16_f32 v233, v18, v19
	ds_write_b128 v166, v[226:229]
	ds_write_b128 v166, v[230:233] offset:64
	ds_read_b128 v[226:229], v167
	ds_read_b128 v[230:233], v167 offset:1152
	s_mov_b32 s20, 0x50000
	v_lshl_add_u64 v[24:25], v[208:209], 0, s[20:21]
	s_mov_b32 s20, 0x54000
	v_lshl_add_u64 v[26:27], v[208:209], 0, s[20:21]
	s_waitcnt lgkmcnt(1)
	global_store_dwordx4 v[24:25], v[226:229], off
	s_waitcnt lgkmcnt(0)
	global_store_dwordx4 v[26:27], v[230:233], off
	s_waitcnt vmcnt(14)
	v_lshlrev_b32_e32 v128, 16, v234
	v_and_b32_e32 v129, 0xffff0000, v234
	v_lshlrev_b32_e32 v130, 16, v235
	v_and_b32_e32 v131, 0xffff0000, v235
	v_lshlrev_b32_e32 v132, 16, v236
	v_and_b32_e32 v133, 0xffff0000, v236
	v_lshlrev_b32_e32 v134, 16, v237
	v_and_b32_e32 v135, 0xffff0000, v237
	v_lshlrev_b32_e32 v234, 16, v238
	v_and_b32_e32 v235, 0xffff0000, v238
	v_lshlrev_b32_e32 v236, 16, v239
	v_and_b32_e32 v237, 0xffff0000, v239
	v_lshlrev_b32_e32 v238, 16, v240
	v_and_b32_e32 v239, 0xffff0000, v240
	v_lshlrev_b32_e32 v240, 16, v241
	v_and_b32_e32 v241, 0xffff0000, v241
	v_max_f32_e32 v128, 0xda24260, v128
	v_max_f32_e32 v129, 0xda24260, v129
	v_max_f32_e32 v130, 0xda24260, v130
	v_max_f32_e32 v131, 0xda24260, v131
	v_max_f32_e32 v132, 0xda24260, v132
	v_max_f32_e32 v133, 0xda24260, v133
	v_max_f32_e32 v134, 0xda24260, v134
	v_max_f32_e32 v135, 0xda24260, v135
	v_max_f32_e32 v234, 0xda24260, v234
	v_max_f32_e32 v235, 0xda24260, v235
	v_max_f32_e32 v236, 0xda24260, v236
	v_max_f32_e32 v237, 0xda24260, v237
	v_max_f32_e32 v238, 0xda24260, v238
	v_max_f32_e32 v239, 0xda24260, v239
	v_max_f32_e32 v240, 0xda24260, v240
	v_max_f32_e32 v241, 0xda24260, v241
	v_pk_mul_f32 v[12:13], v[12:13], v[128:129]
	v_pk_mul_f32 v[14:15], v[14:15], v[130:131]
	v_pk_mul_f32 v[8:9], v[8:9], v[132:133]
	v_pk_mul_f32 v[10:11], v[10:11], v[134:135]
	v_pk_mul_f32 v[4:5], v[4:5], v[234:235]
	v_pk_mul_f32 v[6:7], v[6:7], v[236:237]
	v_pk_mul_f32 v[0:1], v[0:1], v[238:239]
	v_pk_mul_f32 v[2:3], v[2:3], v[240:241]
	v_cvt_pk_bf16_f32 v234, v12, v13
	v_cvt_pk_bf16_f32 v235, v14, v15
	v_cvt_pk_bf16_f32 v236, v8, v9
	v_cvt_pk_bf16_f32 v237, v10, v11
	v_cvt_pk_bf16_f32 v238, v4, v5
	v_cvt_pk_bf16_f32 v239, v6, v7
	v_cvt_pk_bf16_f32 v240, v0, v1
	v_cvt_pk_bf16_f32 v241, v2, v3
	ds_write_b128 v166, v[234:237]
	ds_write_b128 v166, v[238:241] offset:64
	ds_read_b128 v[234:237], v167
	ds_read_b128 v[238:241], v167 offset:1152
	s_mov_b32 s20, 0x58000
	v_lshl_add_u64 v[8:9], v[208:209], 0, s[20:21]
	s_mov_b32 s20, 0x5c000
	v_lshl_add_u64 v[10:11], v[208:209], 0, s[20:21]
	s_and_b64 vcc, exec, s[0:1]
	s_mov_b64 s[0:1], -1
	s_waitcnt lgkmcnt(1)
	global_store_dwordx4 v[8:9], v[234:237], off
	s_waitcnt lgkmcnt(0)
	global_store_dwordx4 v[10:11], v[238:241], off
	s_cbranch_vccnz .LBB0_696
	s_andn2_b64 vcc, exec, s[10:11]
	s_cbranch_vccnz .LBB0_695
	s_barrier
	s_branch .LBB0_695
